# static priority raise for the younger workgroups (blockIdx >= 256) over the attention ticket loop, reset at phase exit
# baseline (speedup 1.0000x reference)
; DI void attn_item(const Params& p, int l, int item, char* lds) {
;     ...
;     const float lam_init = 0.8f - 0.6f * __expf(-0.3f * (float)l);
;     const float lam = __expf(d1) - __expf(d2) + lam_init;
;     float ss = 0.f;
; #pragma unroll
;     for (int vt = 0; vt < 4; ++vt)
; #pragma unroll
;       for (int e = 0; e < 16; ++e) {
;         const int vd = vt * 32 + (e & 3) + 8 * (e >> 2) + 4 * hh;
;         const float o2 = xb[(qh * 128 + vd) * 32 + q];
;         const float o = O[vt][e] - lam * o2; O[vt][e] = o; ss += o * o;
;       }
;     ss += __shfl_xor(ss, 32);
;     const float rstd = rsqrtf(ss * (1.0f / 128.0f) + 1e-5f) * (1.0f - lam_init);
;     const size_t row = (size_t)(qrow0 + qh * 32 + q);
;     const float* sg = p.subln_g + l * 128;
; DI void phase_mix(const Params& p, int l, char* lds) {
;   __shared__ int s_next;
;   if (blockIdx.x < 96) {
;     if (blockIdx.x >= 32) {
;       for (int c2 = 0; c2 < 2; ++c2) chunk_item(p, l, NCH_P + (blockIdx.x - 32) * 2 + c2, lds);
;       __syncthreads();
;     }
;     __builtin_amdgcn_s_setprio(3); rec_item(p, l, blockIdx.x, lds); __builtin_amdgcn_s_setprio(0);
;     if (blockIdx.x >= 32) { const int pis = NCH_P / 2 + (blockIdx.x - 32); phase_o(p, l, pis, pis + 1, 1); }
;   }
;   if (gridDim.x == 512 && blockIdx.x >= 256 && blockIdx.x < 288) return;
;   unsigned* ctr = p.bar + XCD_BAR_WORDS + 64 * l + (blockIdx.x & 7);
;   for (;;) {
;     __syncthreads();
;     if (threadIdx.x == 0) { const int k = (int)atomicAdd(ctr, 1u); s_next = k < 132 ? k * 8 + (int)(blockIdx.x & 7) : 1 << 20; }
;     __syncthreads();
;     const int it = s_next;
;     if (it >= (1 << 20)) break;
;     attn_item(p, l, it, lds);
;   }
.LBB0_569:
	v_readlane_b32 s0, v254, 5
	v_readlane_b32 s1, v254, 6
	s_andn2_b64 vcc, exec, s[0:1]
	s_cbranch_vccnz .LBB0_613
	v_readlane_b32 s0, v251, 0
	s_nop 1
	s_cmp_lt_u32 s0, 0x100
	s_cbranch_scc1 .Lyprio_skip
	s_setprio 1
.Lyprio_skip:
	v_readlane_b32 s20, v255, 2
	v_readlane_b32 s0, v254, 63
	v_readlane_b32 s1, v255, 0
	v_cvt_f32_u32_e32 v0, s20
	s_lshl_b64 s[0:1], s[0:1], 2
	v_readlane_b32 s2, v254, 7
	s_add_u32 s2, s2, s0
	v_mul_f32_e32 v0, 0xbe99999a, v0
	v_mul_f32_e32 v0, 0x3fb8aa3b, v0
	v_exp_f32_e32 v0, v0
	v_readlane_b32 s0, v254, 8
	s_addc_u32 s3, s0, s1
	s_lshl_b32 s96, s20, 7
	v_readlane_b32 s68, v251, 33
	s_lshl_b64 s[0:1], s[96:97], 2
	v_readlane_b32 s72, v251, 37
	v_mov_b32_e32 v2, 0x3f4ccccd
	v_readlane_b32 s73, v251, 38
	s_add_u32 s22, s72, s0
	v_fmamk_f32 v190, v0, 0xbf19999a, v2
	v_readlane_b32 s21, v255, 3
	v_writelane_b32 v254, s2, 63
	v_sub_f32_e32 v191, 1.0, v190
	s_addc_u32 s23, s73, s1
	v_writelane_b32 v255, s3, 0
	v_readlane_b32 s69, v251, 34
	v_readlane_b32 s70, v251, 35
	v_readlane_b32 s71, v251, 36
	v_readlane_b32 s74, v251, 39
	v_readlane_b32 s75, v251, 40
	v_readlane_b32 s76, v251, 41
	v_readlane_b32 s77, v251, 42
	v_readlane_b32 s78, v251, 43
	v_readlane_b32 s79, v251, 44
	v_readlane_b32 s80, v251, 45
	v_readlane_b32 s81, v251, 46
	v_readlane_b32 s82, v251, 47
	v_readlane_b32 s83, v251, 48
	s_branch .LBB0_573

; DI void xcd_barrier(const XcdBarrier& b) {
;   asm volatile("s_waitcnt vmcnt(0)" ::: "memory");
;   __syncthreads();
;   if (threadIdx.x == 0) {
;     unsigned* bar = b.bar;
;     __builtin_amdgcn_s_waitcnt(0);
;     unsigned nloc = b.st[0], nx = b.st[1];
;     if (nloc == 0u) { xcd_barrier_complete(bar, b.x, nloc, nx); b.st[0] = nloc; b.st[1] = nx; }
.LBB0_613:
	s_setprio 0
	s_waitcnt vmcnt(0)
	s_barrier
	s_and_saveexec_b64 s[0:1], s[50:51]
	s_cbranch_execz .LBB0_665
	s_waitcnt vmcnt(0) expcnt(0) lgkmcnt(0)
	ds_read_b32 v3, v210
	ds_read_b32 v2, v211
	s_waitcnt lgkmcnt(1)
	v_cmp_ne_u32_e32 vcc, 0, v3
	s_cbranch_vccnz .LBB0_629
	s_mov_b32 s20, 1
	s_branch .LBB0_617
